# in-proj A now parks 6 stores per wave (third-last row group via v162-165/v190-193, constants re-materialised at K-loop exit), trickled in iterations 2-7
# speedup vs baseline: 1.0140x; 1.0037x over previous
; #define PG8_STAGE(bufoff, gbase, voff) do { _Pragma("unroll") for (int _i = 0; _i < 2; ++_i) \
;         __builtin_amdgcn_global_load_lds((const unsigned*)((const char*)(gbase) + (voff)[_i]), (PG8_LAS unsigned*)(lds + (bufoff) + ldsw + _i * 8192), 16, 0, 0); } while (0)
; #define PG8_LDA(dst, b, h) do { _Pragma("unroll") for (int m = 0; m < 4; ++m) _Pragma("unroll") for (int k = 0; k < 2; ++k) dst[m][k] = *(const PG8_LAS bf16x8*)(lds + PG8_SA(b, h) + aoff + m * 2048 + k * 1024); } while (0)
; #define PG8_LDB(dst, b, h) do { _Pragma("unroll") for (int n = 0; n < 2; ++n) _Pragma("unroll") for (int k = 0; k < 2; ++k) dst[n][k] = *(const PG8_LAS bf16x8*)(lds + PG8_SB(b, h) + boff + n * 2048 + k * 1024); } while (0)
; #define PG8_SCHED __builtin_amdgcn_sched_barrier(0)
;     ...
;         const bool has_next = S.next(ui + 1, nxt);
;         const char* nA = has_next ? (const char*)g.A + (size_t)nxt.pm * tstep : cA; const char* nB = has_next ? (const char*)g.Bt + (size_t)nxt.pn * tstep : cB;
;         for (int t = 0; t < nt; t += 2) {
;             const bool last = (t == nt - 2);
;             const char* a1 = cA + (size_t)(t + 1) * kstep;
;             const char* a2 = last ? nA : cA + (size_t)(t + 2) * kstep; const char* b2 = last ? nB : cB + (size_t)(t + 2) * kstep;
;             const char* a3 = a2 + kstep; const char* b3 = b2 + kstep;
;             PG8_LDB(B0, 0, 0); PG8_LDB(B1, 0, 1); PG8_SCHED; PG8_LDA(At, 0, 0); PG8_STAGE(PG8_SA(1, 1), a1 + hstep, voffA);
.LBB0_205:
	s_ashr_i32 s31, s30, 31
	s_lshl_b64 s[48:49], s[30:31], 19
	s_add_u32 s48, s16, s48
	s_addc_u32 s49, s17, s49
	s_and_b64 s[60:61], s[36:37], exec
	s_cselect_b32 s2, s49, s39
	s_cselect_b32 s31, s48, s38
	s_ashr_i32 s29, s28, 31
	s_lshl_b64 s[60:61], s[28:29], 19
	v_readlane_b32 s76, v253, 18
	v_readlane_b32 s77, v253, 19
	s_add_u32 s78, s76, s60
	s_addc_u32 s79, s77, s61
	s_and_b64 s[60:61], s[36:37], exec
	s_cselect_b32 s29, s79, s73
	s_cselect_b32 s60, s78, s72
	s_add_u32 s38, s38, 0x40080
	s_addc_u32 s39, s39, 0
	s_add_u32 s61, s72, 0x100
	s_addc_u32 s80, s73, 0
	s_mov_b32 s81, -2
	s_cmp_eq_u32 s101, 6
	s_cbranch_scc0 .Lpka_nomove
	v_mov_b32_e32 v162, v214
	v_mov_b32_e32 v163, v215
	v_mov_b32_e32 v164, v216
	v_mov_b32_e32 v165, v217
	v_mov_b32_e32 v190, v218
	v_mov_b32_e32 v191, v219
	v_mov_b32_e32 v192, v220
	v_mov_b32_e32 v193, v221
.Lpka_nomove:
.LBB0_206:
	s_add_u32 s72, s38, 0xfffc0080
	s_addc_u32 s73, s39, -1
	s_add_i32 s82, 0, 0x10000
	s_cmp_eq_u32 s81, 12
	s_cselect_b32 s77, s2, s73
	s_cselect_b32 s76, s31, s72
	s_cselect_b32 s73, s29, s80
	s_cselect_b32 s72, s60, s61
	s_add_i32 s86, 0, 0x14000
	s_waitcnt lgkmcnt(0)
	v_add_u32_e32 v156, s82, v195
	v_add_u32_e32 v183, s86, v195
	ds_read_b128 v[144:147], v156
	ds_read_b128 v[148:151], v156 offset:1024
	ds_read_b128 v[152:155], v156 offset:2048
	ds_read_b128 v[156:159], v156 offset:3072
	ds_read_b128 v[186:189], v183
	ds_read_b128 v[198:201], v183 offset:1024
	ds_read_b128 v[202:205], v183 offset:2048
	ds_read_b128 v[206:209], v183 offset:3072
	v_lshl_add_u64 v[242:243], s[38:39], 0, v[178:179]
	s_add_i32 m0, s63, 0xc000
	ds_read_b128 v[210:213], v197
	ds_read_b128 v[214:217], v197 offset:1024
	ds_read_b128 v[218:221], v197 offset:2048
	ds_read_b128 v[222:225], v197 offset:3072
	ds_read_b128 v[226:229], v197 offset:4096
	ds_read_b128 v[230:233], v197 offset:5120
	ds_read_b128 v[234:237], v197 offset:6144
	ds_read_b128 v[238:241], v197 offset:7168
	global_load_lds_dwordx4 v[242:243], off
	v_lshl_add_u64 v[242:243], s[38:39], 0, v[180:181]
	s_add_i32 m0, s63, 0xe000
	s_nop 0
	global_load_lds_dwordx4 v[242:243], off
	s_mov_b32 s100, 0
	s_cmp_eq_u32 s101, 0
	s_cbranch_scc1 .Lpka_w8a
	s_cmp_lt_i32 s81, 2
	s_cbranch_scc1 .Lpka_w8a
	s_mov_b32 s100, 1
	s_cmp_eq_u32 s101, 6
	s_cbranch_scc1 .Lpka_s0
	s_cmp_eq_u32 s101, 5
	s_cbranch_scc1 .Lpka_s1
	s_cmp_eq_u32 s101, 4
	s_cbranch_scc1 .Lpka_s2
	s_cmp_eq_u32 s101, 3
	s_cbranch_scc1 .Lpka_s3
	s_cmp_eq_u32 s101, 2
	s_cbranch_scc1 .Lpka_s4
	global_store_dwordx4 v[254:255], v[12:15], off offset:64
	s_branch .Lpka_w9a
.Lpka_s0:
	global_store_dwordx4 v[254:255], v[162:165], off
	s_branch .Lpka_w9a
.Lpka_s1:
	global_store_dwordx4 v[254:255], v[190:193], off offset:64
	v_add_co_u32_e32 v254, vcc, s88, v254
	s_nop 1
	v_addc_co_u32_e32 v255, vcc, 0, v255, vcc
	s_branch .Lpka_w9a

; #define PG8_STAGE(bufoff, gbase, voff) do { _Pragma("unroll") for (int _i = 0; _i < 2; ++_i) \
;         __builtin_amdgcn_global_load_lds((const unsigned*)((const char*)(gbase) + (voff)[_i]), (PG8_LAS unsigned*)(lds + (bufoff) + ldsw + _i * 8192), 16, 0, 0); } while (0)
; #define PG8_LDA(dst, b, h) do { _Pragma("unroll") for (int m = 0; m < 4; ++m) _Pragma("unroll") for (int k = 0; k < 2; ++k) dst[m][k] = *(const PG8_LAS bf16x8*)(lds + PG8_SA(b, h) + aoff + m * 2048 + k * 1024); } while (0)
; #define PG8_WAIT_V(n) asm volatile("s_waitcnt vmcnt(" #n ")" ::: "memory")
; #define PG8_WAIT_L(n) asm volatile("s_waitcnt lgkmcnt(" #n ")" ::: "memory")
; #define PG8_BAR __builtin_amdgcn_s_barrier()
; #define PG8_SCHED __builtin_amdgcn_sched_barrier(0)
;     ...
;             PG8_WAIT_V(8); PG8_WAIT_L(0); PG8_BAR; PG8_MMA(0, 0, At, B0); PG8_MMA(0, 1, At, B1); PG8_BAR; PG8_SCHED;
;             PG8_LDA(At, 1, 1); PG8_STAGE(PG8_SB(1, 0), b3, voffB); PG8_STAGE(PG8_SB(1, 1), b3 + hstepB, voffB); PG8_STAGE(PG8_SA(1, 0), a3, voffA);
;             PG8_WAIT_V(8); PG8_WAIT_L(0); PG8_BAR; PG8_MMA(1, 0, At, B0); PG8_MMA(1, 1, At, B1); PG8_BAR; PG8_SCHED;
;         }
;         if constexpr (ALIGN_EPI) { if (wr == 0) PG8_BAR; }
.Lpka_dc:
	s_waitcnt lgkmcnt(0)
	s_barrier
	s_setprio 1
	s_waitcnt lgkmcnt(0)
	v_mfma_f32_16x16x32_bf16 v[132:135], v[144:147], v[210:213], v[132:135]
	v_mfma_f32_16x16x32_bf16 v[128:131], v[152:155], v[210:213], v[128:131]
	v_mfma_f32_16x16x32_bf16 v[116:119], v[144:147], v[218:221], v[116:119]
	v_mfma_f32_16x16x32_bf16 v[112:115], v[152:155], v[218:221], v[112:115]
	v_mfma_f32_16x16x32_bf16 v[100:103], v[144:147], v[226:229], v[100:103]
	v_mfma_f32_16x16x32_bf16 v[96:99], v[152:155], v[226:229], v[96:99]
	v_mfma_f32_16x16x32_bf16 v[84:87], v[144:147], v[234:237], v[84:87]
	v_mfma_f32_16x16x32_bf16 v[80:83], v[152:155], v[234:237], v[80:83]
	v_mfma_f32_16x16x32_bf16 v[132:135], v[148:151], v[214:217], v[132:135]
	v_mfma_f32_16x16x32_bf16 v[128:131], v[156:159], v[214:217], v[128:131]
	v_mfma_f32_16x16x32_bf16 v[116:119], v[148:151], v[222:225], v[116:119]
	v_mfma_f32_16x16x32_bf16 v[112:115], v[156:159], v[222:225], v[112:115]
	v_mfma_f32_16x16x32_bf16 v[100:103], v[148:151], v[230:233], v[100:103]
	v_mfma_f32_16x16x32_bf16 v[96:99], v[156:159], v[230:233], v[96:99]
	v_mfma_f32_16x16x32_bf16 v[84:87], v[148:151], v[238:241], v[84:87]
	v_mfma_f32_16x16x32_bf16 v[80:83], v[156:159], v[238:241], v[80:83]
	s_setprio 0
	s_setprio 1
	v_mfma_f32_16x16x32_bf16 v[140:143], v[186:189], v[210:213], v[140:143]
	v_mfma_f32_16x16x32_bf16 v[136:139], v[202:205], v[210:213], v[136:139]
	v_mfma_f32_16x16x32_bf16 v[124:127], v[186:189], v[218:221], v[124:127]
	v_mfma_f32_16x16x32_bf16 v[120:123], v[202:205], v[218:221], v[120:123]
	v_mfma_f32_16x16x32_bf16 v[108:111], v[186:189], v[226:229], v[108:111]
	v_mfma_f32_16x16x32_bf16 v[104:107], v[202:205], v[226:229], v[104:107]
	v_mfma_f32_16x16x32_bf16 v[92:95], v[186:189], v[234:237], v[92:95]
	v_mfma_f32_16x16x32_bf16 v[88:91], v[202:205], v[234:237], v[88:91]
	v_mfma_f32_16x16x32_bf16 v[140:143], v[198:201], v[214:217], v[140:143]
	v_mfma_f32_16x16x32_bf16 v[136:139], v[206:209], v[214:217], v[136:139]
	v_mfma_f32_16x16x32_bf16 v[124:127], v[198:201], v[222:225], v[124:127]
	v_mfma_f32_16x16x32_bf16 v[120:123], v[206:209], v[222:225], v[120:123]
	v_mfma_f32_16x16x32_bf16 v[108:111], v[198:201], v[230:233], v[108:111]
	v_mfma_f32_16x16x32_bf16 v[104:107], v[206:209], v[230:233], v[104:107]
	v_mfma_f32_16x16x32_bf16 v[92:95], v[198:201], v[238:241], v[92:95]
	v_mfma_f32_16x16x32_bf16 v[88:91], v[206:209], v[238:241], v[88:91]
	s_setprio 0
	s_barrier
	s_add_i32 s76, s82, s15
	v_lshl_add_u64 v[242:243], v[242:243], 0, s[4:5]
	s_mov_b32 m0, s76
	ds_read_b128 v[210:213], v197 offset:49152
	ds_read_b128 v[214:217], v197 offset:50176
	ds_read_b128 v[218:221], v197 offset:51200
	ds_read_b128 v[222:225], v197 offset:52224
	ds_read_b128 v[226:229], v197 offset:53248
	ds_read_b128 v[230:233], v197 offset:54272
	ds_read_b128 v[234:237], v197 offset:55296
	ds_read_b128 v[238:241], v197 offset:56320
	global_load_lds_dwordx4 v[242:243], off
	s_add_i32 m0, s76, 0x2000
	s_add_u32 s72, s72, 0x10080
	v_lshl_add_u64 v[242:243], v[244:245], 0, s[4:5]
	s_addc_u32 s73, s73, 0
	s_add_i32 s76, s83, s15
	global_load_lds_dwordx4 v[242:243], off
	v_lshl_add_u64 v[242:243], s[72:73], 0, v[170:171]
	s_mov_b32 m0, s76
	s_nop 0
	global_load_lds_dwordx4 v[242:243], off
	v_lshl_add_u64 v[242:243], s[72:73], 0, v[166:167]
	s_add_i32 m0, s76, 0x2000
	s_nop 0
	global_load_lds_dwordx4 v[242:243], off
	v_lshl_add_u64 v[242:243], v[246:247], 0, s[4:5]
	s_mov_b32 m0, s74
	s_nop 0
	global_load_lds_dwordx4 v[242:243], off
	v_lshl_add_u64 v[242:243], v[248:249], 0, s[4:5]
	s_mov_b32 m0, s75
	s_nop 0
	global_load_lds_dwordx4 v[242:243], off
	s_waitcnt vmcnt(8)
	s_waitcnt lgkmcnt(0)
	s_barrier
	s_setprio 1
	s_waitcnt lgkmcnt(0)
	v_mfma_f32_16x16x32_bf16 v[68:71], v[144:147], v[210:213], v[68:71]
	v_mfma_f32_16x16x32_bf16 v[64:67], v[152:155], v[210:213], v[64:67]
	v_mfma_f32_16x16x32_bf16 v[52:55], v[144:147], v[218:221], v[52:55]
	v_mfma_f32_16x16x32_bf16 v[48:51], v[152:155], v[218:221], v[48:51]
	v_mfma_f32_16x16x32_bf16 v[36:39], v[144:147], v[226:229], v[36:39]
	v_mfma_f32_16x16x32_bf16 v[32:35], v[152:155], v[226:229], v[32:35]
	v_mfma_f32_16x16x32_bf16 v[20:23], v[144:147], v[234:237], v[20:23]
	v_mfma_f32_16x16x32_bf16 v[16:19], v[152:155], v[234:237], v[16:19]
	v_mfma_f32_16x16x32_bf16 v[68:71], v[148:151], v[214:217], v[68:71]
	v_mfma_f32_16x16x32_bf16 v[64:67], v[156:159], v[214:217], v[64:67]
	v_mfma_f32_16x16x32_bf16 v[52:55], v[148:151], v[222:225], v[52:55]
	v_mfma_f32_16x16x32_bf16 v[48:51], v[156:159], v[222:225], v[48:51]
	v_mfma_f32_16x16x32_bf16 v[36:39], v[148:151], v[230:233], v[36:39]
	v_mfma_f32_16x16x32_bf16 v[32:35], v[156:159], v[230:233], v[32:35]
	v_mfma_f32_16x16x32_bf16 v[20:23], v[148:151], v[238:241], v[20:23]
	v_mfma_f32_16x16x32_bf16 v[16:19], v[156:159], v[238:241], v[16:19]
	s_setprio 0
	s_setprio 1
	v_mfma_f32_16x16x32_bf16 v[76:79], v[186:189], v[210:213], v[76:79]
	v_mfma_f32_16x16x32_bf16 v[72:75], v[202:205], v[210:213], v[72:75]
	v_mfma_f32_16x16x32_bf16 v[60:63], v[186:189], v[218:221], v[60:63]
	v_mfma_f32_16x16x32_bf16 v[56:59], v[202:205], v[218:221], v[56:59]
	v_mfma_f32_16x16x32_bf16 v[44:47], v[186:189], v[226:229], v[44:47]
	v_mfma_f32_16x16x32_bf16 v[40:43], v[202:205], v[226:229], v[40:43]
	v_mfma_f32_16x16x32_bf16 v[24:27], v[186:189], v[234:237], v[24:27]
	v_mfma_f32_16x16x32_bf16 v[28:31], v[202:205], v[234:237], v[28:31]
	v_mfma_f32_16x16x32_bf16 v[76:79], v[198:201], v[214:217], v[76:79]
	v_mfma_f32_16x16x32_bf16 v[72:75], v[206:209], v[214:217], v[72:75]
	v_mfma_f32_16x16x32_bf16 v[60:63], v[198:201], v[222:225], v[60:63]
	v_mfma_f32_16x16x32_bf16 v[56:59], v[206:209], v[222:225], v[56:59]
	v_mfma_f32_16x16x32_bf16 v[44:47], v[198:201], v[230:233], v[44:47]
	v_mfma_f32_16x16x32_bf16 v[40:43], v[206:209], v[230:233], v[40:43]
	v_mfma_f32_16x16x32_bf16 v[24:27], v[198:201], v[238:241], v[24:27]
	v_mfma_f32_16x16x32_bf16 v[28:31], v[206:209], v[238:241], v[28:31]
	s_setprio 0
	s_barrier
	s_sub_u32 s101, s101, s100
	s_add_i32 s81, s81, 2
	s_add_u32 s38, s38, 0x100
	s_addc_u32 s39, s39, 0
	s_add_u32 s61, s61, 0x100
	s_addc_u32 s80, s80, 0
	s_cmp_gt_u32 s81, 13
	s_cbranch_scc0 .LBB0_206
	v_mov_b32_e32 v162, 0x500
	v_mov_b32_e32 v163, 0
	v_mov_b32_e32 v164, 0x4ff
	v_mov_b32_e32 v165, 0
	v_mov_b32_e32 v190, 0x358637bd
	v_mov_b32_e32 v191, 1
	v_mov_b32_e32 v192, 0x300
	v_mov_b32_e32 v193, 0x200
	s_and_b64 vcc, exec, s[22:23]
	s_cbranch_vccz .LBB0_209
	s_barrier

; __device__ __forceinline__ float sum_x16(float v) { float a, b; swap16(v, a, b); return a + b; }
; __device__ __forceinline__ float sum_x32(float v) { float a, b; swap32(v, a, b); return a + b; }
; __device__ __forceinline__ void st16_wt(void* p, u32x4 v) { if (WT_STORES) asm volatile("global_store_dwordx4 %0, %1, off sc1\n\ts_nop 1" :: "v"(p), "v"(v) : "memory"); else *(u32x4*)p = v; }
; __device__ __forceinline__ unsigned cvt_pk_bf16(float lo, float hi) { unsigned r; asm volatile("v_cvt_pk_bf16_f32 %0, %1, %2" : "=v"(r) : "v"(lo), "v"(hi)); return r; }
;     __device__ __forceinline__ void operator()(const f32x4 (&acc)[2][2][4][2], const Unit& u, int wr, int wc, int fr, int fq, const bool reuse, PG8_LAS float* rscr, PG8_LAS const float* gains) const {
;     ...
; #pragma unroll
;         for (int ai = 0; ai < 2; ++ai)
; #pragma unroll
;             for (int m = 0; m < 4; ++m) {
;                 const int r = u.pm * BM + ai * HALF + wr * 64 + m * 16 + fr;
;                 const float rsv = (MODE == 0) ? 1.0f : rsvv[ai][m];
;                 f32x4 v[2][2];
; #pragma unroll
;                 for (int bj = 0; bj < 2; ++bj)
; #pragma unroll
;                     for (int n = 0; n < 2; ++n) v[bj][n] = acc[ai][bj][m][n] * rsv;
;                 if (type < 2) {
;                     float ss = 0.f;
; #pragma unroll
;                     for (int bj = 0; bj < 2; ++bj)
; #pragma unroll
;                         for (int n = 0; n < 2; ++n) { const f32x4 x = v[bj][n]; ss += (x[0] * x[0] + x[1] * x[1]) + (x[2] * x[2] + x[3] * x[3]); }
;                     ss = sum_x16(ss); ss = sum_x32(ss);
;                     const float inv = __builtin_amdgcn_rsqf(ss * (1.0f / 64.0f) + RMS_EPS);
; #pragma unroll
;                     for (int bj = 0; bj < 2; ++bj)
; #pragma unroll
;                         for (int n = 0; n < 2; ++n) v[bj][n] = v[bj][n] * gv[bj][n] * inv;
;                 }
;                 bf16_t* p = p0 + (size_t)(8 * ai + m) * step16;
; #pragma unroll
;                 for (int bj = 0; bj < 2; ++bj) { u32x4 w; w.x = cvt_pk_bf16(v[bj][0][0], v[bj][0][1]); w.y = cvt_pk_bf16(v[bj][0][2], v[bj][0][3]); w.z = cvt_pk_bf16(v[bj][1][0], v[bj][1][1]); w.w = cvt_pk_bf16(v[bj][1][2], v[bj][1][3]);
;                     st16_wt(p + 32 * bj, w); }
.LBB0_242:
	s_nop 0
	v_lshl_add_u64 v[64:65], v[80:81], 0, s[88:89]
	v_mov_b32_e32 v254, v64
	v_mov_b32_e32 v255, v65
	s_and_b64 vcc, exec, s[38:39]
	v_cvt_pk_bf16_f32 v52, v52, v53
	v_cvt_pk_bf16_f32 v53, v54, v55
	v_cvt_pk_bf16_f32 v54, v48, v49
	v_cvt_pk_bf16_f32 v55, v50, v51
	v_mov_b32_e32 v214, v52
	v_mov_b32_e32 v215, v53
	v_mov_b32_e32 v216, v54
	v_mov_b32_e32 v217, v55
	v_cvt_pk_bf16_f32 v48, v60, v61
	v_cvt_pk_bf16_f32 v49, v62, v63
	v_cvt_pk_bf16_f32 v50, v56, v57
	v_cvt_pk_bf16_f32 v51, v58, v59
	v_mov_b32_e32 v218, v48
	v_mov_b32_e32 v219, v49
	v_mov_b32_e32 v220, v50
	v_mov_b32_e32 v221, v51
	s_cbranch_vccnz .LBB0_244
	s_nop 0
	v_mul_f32_e32 v48, v37, v37
	v_mul_f32_e32 v49, v39, v39
	v_fmac_f32_e32 v48, v36, v36
	v_fmac_f32_e32 v49, v38, v38
	v_add_f32_e32 v48, v48, v49
	v_mul_f32_e32 v49, v33, v33
	v_mul_f32_e32 v50, v35, v35
	v_fmac_f32_e32 v49, v32, v32
	v_fmac_f32_e32 v50, v34, v34
	v_add_f32_e32 v49, v49, v50
	v_add_f32_e32 v48, v48, v49
	v_mul_f32_e32 v49, v45, v45
	v_mul_f32_e32 v50, v47, v47
	v_fmac_f32_e32 v49, v44, v44
	v_fmac_f32_e32 v50, v46, v46
	v_add_f32_e32 v49, v49, v50
	v_add_f32_e32 v48, v48, v49
	v_mul_f32_e32 v49, v41, v41
	v_mul_f32_e32 v50, v43, v43
	v_fmac_f32_e32 v49, v40, v40
	v_fmac_f32_e32 v50, v42, v42
	v_add_f32_e32 v49, v49, v50
	v_add_f32_e32 v48, v48, v49
	v_mov_b32_e32 v49, v48
	s_nop 1
	v_permlane16_swap_b32_e32 v48, v49
	v_add_f32_e32 v48, v48, v49
	v_mov_b32_e32 v49, v48
	s_nop 1
	v_permlane32_swap_b32_e32 v48, v49
	v_add_f32_e32 v48, v48, v49
	v_fmamk_f32 v48, v48, 0x3c800000, v190
	v_rsq_f32_e32 v48, v48
	s_waitcnt lgkmcnt(0)
	v_pk_mul_f32 v[38:39], v[38:39], v[158:159]
	v_pk_mul_f32 v[36:37], v[36:37], v[156:157]
	v_pk_mul_f32 v[34:35], v[34:35], v[154:155]
	v_pk_mul_f32 v[32:33], v[32:33], v[152:153]
	v_pk_mul_f32 v[46:47], v[46:47], v[150:151]
	v_pk_mul_f32 v[44:45], v[44:45], v[148:149]
	v_pk_mul_f32 v[42:43], v[42:43], v[146:147]
	v_pk_mul_f32 v[40:41], v[40:41], v[144:145]
	v_pk_mul_f32 v[38:39], v[38:39], v[48:49] op_sel_hi:[1,0]
	v_pk_mul_f32 v[36:37], v[36:37], v[48:49] op_sel_hi:[1,0]
	v_pk_mul_f32 v[34:35], v[34:35], v[48:49] op_sel_hi:[1,0]
	v_pk_mul_f32 v[32:33], v[32:33], v[48:49] op_sel_hi:[1,0]
	v_pk_mul_f32 v[46:47], v[46:47], v[48:49] op_sel_hi:[1,0]
	v_pk_mul_f32 v[44:45], v[44:45], v[48:49] op_sel_hi:[1,0]
	v_pk_mul_f32 v[42:43], v[42:43], v[48:49] op_sel_hi:[1,0]
	v_pk_mul_f32 v[40:41], v[40:41], v[48:49] op_sel_hi:[1,0]
.LBB0_244:
	s_nop 0
	v_lshl_add_u64 v[48:49], v[64:65], 0, s[88:89]
	s_and_b64 vcc, exec, s[38:39]
	v_cvt_pk_bf16_f32 v36, v36, v37
	v_cvt_pk_bf16_f32 v37, v38, v39
	v_cvt_pk_bf16_f32 v38, v32, v33
	v_cvt_pk_bf16_f32 v39, v34, v35
	v_mov_b32_e32 v0, v36
	v_mov_b32_e32 v1, v37
	v_mov_b32_e32 v2, v38
	v_mov_b32_e32 v3, v39
	v_cvt_pk_bf16_f32 v32, v44, v45
	v_cvt_pk_bf16_f32 v33, v46, v47
	v_cvt_pk_bf16_f32 v34, v40, v41
	v_cvt_pk_bf16_f32 v35, v42, v43
	v_mov_b32_e32 v4, v32
	v_mov_b32_e32 v5, v33
	v_mov_b32_e32 v6, v34
	v_mov_b32_e32 v7, v35
	s_cbranch_vccnz .LBB0_246
	s_nop 0
	v_mul_f32_e32 v32, v21, v21
	v_mul_f32_e32 v33, v23, v23
	v_fmac_f32_e32 v32, v20, v20
	v_fmac_f32_e32 v33, v22, v22
	v_add_f32_e32 v32, v32, v33
	v_mul_f32_e32 v33, v17, v17
	v_mul_f32_e32 v34, v19, v19
	v_fmac_f32_e32 v33, v16, v16
	v_fmac_f32_e32 v34, v18, v18
	v_add_f32_e32 v33, v33, v34
	v_add_f32_e32 v32, v32, v33
	v_mul_f32_e32 v33, v25, v25
	v_mul_f32_e32 v34, v27, v27
	v_fmac_f32_e32 v33, v24, v24
	v_fmac_f32_e32 v34, v26, v26
	v_add_f32_e32 v33, v33, v34
	v_add_f32_e32 v32, v32, v33
	v_mul_f32_e32 v33, v29, v29
	v_mul_f32_e32 v34, v31, v31
	v_fmac_f32_e32 v33, v28, v28
	v_fmac_f32_e32 v34, v30, v30
	v_add_f32_e32 v33, v33, v34
	v_add_f32_e32 v32, v32, v33
	v_mov_b32_e32 v33, v32
	s_nop 1
	v_permlane16_swap_b32_e32 v32, v33
	v_add_f32_e32 v32, v32, v33
	v_mov_b32_e32 v33, v32
	s_nop 1
	v_permlane32_swap_b32_e32 v32, v33
	v_add_f32_e32 v32, v32, v33
	v_fmamk_f32 v32, v32, 0x3c800000, v190
	v_rsq_f32_e32 v32, v32
	s_waitcnt lgkmcnt(0)
	v_pk_mul_f32 v[22:23], v[22:23], v[158:159]
	v_pk_mul_f32 v[20:21], v[20:21], v[156:157]
	v_pk_mul_f32 v[18:19], v[18:19], v[154:155]
	v_pk_mul_f32 v[16:17], v[16:17], v[152:153]
	v_pk_mul_f32 v[26:27], v[26:27], v[150:151]
	v_pk_mul_f32 v[24:25], v[24:25], v[148:149]
	v_pk_mul_f32 v[30:31], v[30:31], v[146:147]
	v_pk_mul_f32 v[28:29], v[28:29], v[144:145]
	v_pk_mul_f32 v[22:23], v[22:23], v[32:33] op_sel_hi:[1,0]
	v_pk_mul_f32 v[20:21], v[20:21], v[32:33] op_sel_hi:[1,0]
	v_pk_mul_f32 v[18:19], v[18:19], v[32:33] op_sel_hi:[1,0]
	v_pk_mul_f32 v[16:17], v[16:17], v[32:33] op_sel_hi:[1,0]
	v_pk_mul_f32 v[26:27], v[26:27], v[32:33] op_sel_hi:[1,0]
	v_pk_mul_f32 v[24:25], v[24:25], v[32:33] op_sel_hi:[1,0]
	v_pk_mul_f32 v[30:31], v[30:31], v[32:33] op_sel_hi:[1,0]
	v_pk_mul_f32 v[28:29], v[28:29], v[32:33] op_sel_hi:[1,0]
; __device__ __forceinline__ float wave_sum(float v) { v += dpp_mov<0xB1>(v); v += dpp_mov<0x4E>(v); v += dpp_mov<0x141>(v); v += dpp_mov<0x140>(v); v = sum_x16(v); return sum_x32(v); }
; __device__ __forceinline__ void st16_wt(void* p, u32x4 v) { if (WT_STORES) asm volatile("global_store_dwordx4 %0, %1, off sc1\n\ts_nop 1" :: "v"(p), "v"(v) : "memory"); else *(u32x4*)p = v; }
;     __device__ __forceinline__ void side_finish(const Side& s, int lane) const {
;         if (MODE == 0 && s.row < xrows) {
;             float q = 0.f;
; #pragma unroll
;             for (int j = 0; j < 4; ++j) q += (s.v[j][0] * s.v[j][0] + s.v[j][1] * s.v[j][1]) + (s.v[j][2] * s.v[j][2] + s.v[j][3] * s.v[j][3]);
;             const float rstd = __builtin_amdgcn_rsqf(wave_sum(q) * (1.0f / 1024.0f) + 1e-6f);
;             const bool odd = lane & 1;
;             bf16_t* orow = xd + (size_t)s.row * 1024 + 4 * (lane & ~1);
; #pragma unroll
;             for (int jp = 0; jp < 2; ++jp) {
;                 const int ja = 2 * jp, jb = 2 * jp + 1;
;                 const unsigned pax = cvt_pk_bf16(s.v[ja][0] * rstd, s.v[ja][1] * rstd), pay = cvt_pk_bf16(s.v[ja][2] * rstd, s.v[ja][3] * rstd);
;                 const unsigned pbx = cvt_pk_bf16(s.v[jb][0] * rstd, s.v[jb][1] * rstd), pby = cvt_pk_bf16(s.v[jb][2] * rstd, s.v[jb][3] * rstd);
;                 const unsigned rx = (unsigned)__builtin_amdgcn_update_dpp(0, (int)(odd ? pax : pbx), 0xB1, 0xF, 0xF, true), ry = (unsigned)__builtin_amdgcn_update_dpp(0, (int)(odd ? pay : pby), 0xB1, 0xF, 0xF, true);
;                 u32x4 w; w.x = odd ? rx : pax; w.y = odd ? ry : pay; w.z = odd ? pbx : rx; w.w = odd ? pby : ry;
;                 *(u32x4*)(orow + (odd ? 256 * jb : 256 * ja)) = w;
;     __device__ __forceinline__ void operator()(const f32x4 (&acc)[2][2][4][2], const Unit& u, int wr, int wc, int fr, int fq, const bool reuse, PG8_LAS float* rscr, PG8_LAS const float* gains) const {
;     ...
;                 bf16_t* p = p0 + (size_t)(8 * ai + m) * step16;
; #pragma unroll
;                 for (int bj = 0; bj < 2; ++bj) { u32x4 w; w.x = cvt_pk_bf16(v[bj][0][0], v[bj][0][1]); w.y = cvt_pk_bf16(v[bj][0][2], v[bj][0][3]); w.z = cvt_pk_bf16(v[bj][1][0], v[bj][1][1]); w.w = cvt_pk_bf16(v[bj][1][2], v[bj][1][3]);
;                     st16_wt(p + 32 * bj, w); }
.LBB0_246:
	s_nop 0
	v_lshl_add_u64 v[32:33], v[48:49], 0, s[88:89]
	s_andn2_b64 vcc, exec, s[80:81]
	v_cvt_pk_bf16_f32 v20, v20, v21
	v_cvt_pk_bf16_f32 v21, v22, v23
	v_cvt_pk_bf16_f32 v22, v16, v17
	v_cvt_pk_bf16_f32 v23, v18, v19
	v_mov_b32_e32 v8, v20
	v_mov_b32_e32 v9, v21
	v_mov_b32_e32 v10, v22
	v_mov_b32_e32 v11, v23
	v_cvt_pk_bf16_f32 v16, v24, v25
	v_cvt_pk_bf16_f32 v17, v26, v27
	v_cvt_pk_bf16_f32 v18, v28, v29
	v_cvt_pk_bf16_f32 v19, v30, v31
	v_mov_b32_e32 v12, v16
	v_mov_b32_e32 v13, v17
	v_mov_b32_e32 v14, v18
	v_mov_b32_e32 v15, v19
	s_mov_b32 s101, 6
	s_cbranch_vccnz .LBB0_248
	s_waitcnt vmcnt(10)
	v_mul_f32_e32 v16, v211, v211
	v_mul_f32_e32 v17, v213, v213
	v_fmac_f32_e32 v16, v210, v210
	v_fmac_f32_e32 v17, v212, v212
	v_add_f32_e32 v16, v16, v17
	v_mul_f32_e32 v17, v207, v207
	v_mul_f32_e32 v18, v209, v209
	v_fmac_f32_e32 v17, v206, v206
	v_fmac_f32_e32 v18, v208, v208
	v_add_f32_e32 v17, v17, v18
	v_add_f32_e32 v16, v17, v16
	v_mul_f32_e32 v17, v203, v203
	v_mul_f32_e32 v18, v205, v205
	v_fmac_f32_e32 v17, v202, v202
	v_fmac_f32_e32 v18, v204, v204
	v_add_f32_e32 v17, v17, v18
	v_add_f32_e32 v16, v17, v16
	v_mul_f32_e32 v17, v199, v199
	v_mul_f32_e32 v18, v201, v201
	v_fmac_f32_e32 v17, v198, v198
	v_fmac_f32_e32 v18, v200, v200
	v_add_f32_e32 v17, v17, v18
	v_add_f32_e32 v16, v17, v16
	s_ashr_i32 s77, s76, 31
	s_lshl_b64 s[12:13], s[76:77], 11
	v_add_f32_dpp v16, v16, v16 quad_perm:[1,0,3,2] row_mask:0xf bank_mask:0xf bound_ctrl:1
	v_lshl_add_u64 v[20:21], v[176:177], 0, s[12:13]
	v_mov_b32_e32 v183, v161
	v_add_f32_dpp v16, v16, v16 quad_perm:[2,3,0,1] row_mask:0xf bank_mask:0xf bound_ctrl:1
	v_mov_b32_e32 v185, v161
	s_nop 0
	v_add_f32_dpp v16, v16, v16 row_half_mirror row_mask:0xf bank_mask:0xf bound_ctrl:1
	s_nop 1
	v_add_f32_dpp v16, v16, v16 row_mirror row_mask:0xf bank_mask:0xf bound_ctrl:1
	v_mov_b32_e32 v17, v16
	s_nop 1
	v_permlane16_swap_b32_e32 v16, v17
	v_add_f32_e32 v16, v16, v17
	v_mov_b32_e32 v17, v16
	s_nop 1
	v_permlane32_swap_b32_e32 v16, v17
	v_add_f32_e32 v16, v16, v17
	v_fmamk_f32 v16, v16, 0x3a800000, v190
	v_rsq_f32_e32 v24, v16
	s_nop 0
	v_mul_f32_e32 v16, v210, v24
	v_mul_f32_e32 v17, v211, v24
	v_cvt_pk_bf16_f32 v16, v16, v17
	v_mul_f32_e32 v17, v212, v24
	v_mul_f32_e32 v18, v213, v24
	v_cvt_pk_bf16_f32 v17, v17, v18
	v_mul_f32_e32 v18, v206, v24
	v_mul_f32_e32 v19, v207, v24
	v_cvt_pk_bf16_f32 v18, v18, v19
	v_mul_f32_e32 v19, v208, v24
	v_mul_f32_e32 v22, v209, v24
	v_cvt_pk_bf16_f32 v19, v19, v22
	v_cndmask_b32_e64 v22, v16, v18, s[34:35]
	v_cndmask_b32_e64 v23, v17, v19, s[34:35]
	s_nop 0
	v_mov_b32_dpp v22, v22 quad_perm:[1,0,3,2] row_mask:0xf bank_mask:0xf bound_ctrl:1
	v_mov_b32_dpp v23, v23 quad_perm:[1,0,3,2] row_mask:0xf bank_mask:0xf bound_ctrl:1
	v_cndmask_b32_e64 v16, v22, v16, s[34:35]
	v_cndmask_b32_e64 v17, v23, v17, s[34:35]
	v_cndmask_b32_e64 v18, v18, v22, s[34:35]
	v_cndmask_b32_e64 v19, v19, v23, s[34:35]
	v_lshl_add_u64 v[22:23], v[20:21], 0, v[182:183]
	global_store_dwordx4 v[22:23], v[16:19], off
	v_mul_f32_e32 v22, v201, v24
	v_lshl_add_u64 v[20:21], v[20:21], 0, v[184:185]
	v_mul_f32_e32 v16, v202, v24
	v_mul_f32_e32 v17, v203, v24
	v_cvt_pk_bf16_f32 v16, v16, v17
	v_mul_f32_e32 v17, v204, v24
	v_mul_f32_e32 v18, v205, v24
	v_cvt_pk_bf16_f32 v17, v17, v18
	v_mul_f32_e32 v18, v198, v24
	v_mul_f32_e32 v19, v199, v24
	v_cvt_pk_bf16_f32 v18, v18, v19
	v_mul_f32_e32 v19, v200, v24
	v_cvt_pk_bf16_f32 v19, v19, v22
	v_cndmask_b32_e64 v22, v16, v18, s[34:35]
	v_cndmask_b32_e64 v23, v17, v19, s[34:35]
	s_nop 0
	v_mov_b32_dpp v22, v22 quad_perm:[1,0,3,2] row_mask:0xf bank_mask:0xf bound_ctrl:1
	v_mov_b32_dpp v23, v23 quad_perm:[1,0,3,2] row_mask:0xf bank_mask:0xf bound_ctrl:1
	v_cndmask_b32_e64 v16, v22, v16, s[34:35]
	v_cndmask_b32_e64 v17, v23, v17, s[34:35]
	v_cndmask_b32_e64 v18, v18, v22, s[34:35]
	v_cndmask_b32_e64 v19, v19, v23, s[34:35]
	global_store_dwordx4 v[20:21], v[16:19], off

; #define PG8_ZERO4(x) do { unsigned long long z0_, z1_; asm volatile("v_mov_b64 %0, 0\n\tv_mov_b64 %1, 0" : "=v"(z0_), "=v"(z1_)); typedef unsigned long long u64x2_ __attribute__((ext_vector_type(2))); (x) = __builtin_bit_cast(f32x4, (u64x2_){z0_, z1_}); } while (0)
; #define PG8_WAIT_V(n) asm volatile("s_waitcnt vmcnt(" #n ")" ::: "memory")
; #define PG8_BAR __builtin_amdgcn_s_barrier()
;     ...
;         if (!has_next) break;
; #pragma unroll
;         for (int a = 0; a < 2; ++a)
; #pragma unroll
;             for (int b = 0; b < 2; ++b)
; #pragma unroll
;                 for (int m = 0; m < 4; ++m)
; #pragma unroll
;                     for (int n = 0; n < 2; ++n) PG8_ZERO4(acc[a][b][m][n]);
;         cur = nxt; cA = nA; cB = nB; ++ui;
;         if constexpr (ALIGN_EPI) { if (wr == 1) PG8_BAR; }
;     }
;     PG8_WAIT_V(0);
;     if constexpr (!ALIGN_EPI) { if (wr == 0) PG8_BAR; }
;     PG8_BAR;
.LBB0_253:
	s_cmp_eq_u32 s101, 0
	s_cbranch_scc1 .Lpka_fd
	global_store_dwordx4 v[254:255], v[214:217], off
	global_store_dwordx4 v[254:255], v[218:221], off offset:64
	v_add_co_u32_e32 v254, vcc, s88, v254
	s_nop 1
	v_addc_co_u32_e32 v255, vcc, 0, v255, vcc
	global_store_dwordx4 v[254:255], v[0:3], off
	global_store_dwordx4 v[254:255], v[4:7], off offset:64
	v_add_co_u32_e32 v254, vcc, s88, v254
	s_nop 1
	v_addc_co_u32_e32 v255, vcc, 0, v255, vcc
	global_store_dwordx4 v[254:255], v[8:11], off
	global_store_dwordx4 v[254:255], v[12:15], off offset:64
	s_mov_b32 s101, 0
